# attention tile loop: the four per-tile LDS-DMA issues moved from the post-barrier burst into QK/PV MFMA gaps (plus softmax exps interleaved in PV shadows)
# speedup vs baseline: 1.0061x; 1.0048x over previous
.LBB0_281:
	s_mov_b32 s48, s0
	s_cmp_lt_u32 s47, s44
	s_cbranch_scc0 .Lmy_a_drain
	s_waitcnt vmcnt(4)
	s_barrier
	s_branch .Lmy_a_go

.Lmy_a_go:
	s_lshl_b32 s2, s48, 14
	s_lshl_b32 s52, s49, 14
	s_add_i32 s52, s4, s52
	s_add_i32 s53, s52, 0x2000
	s_add_i32 s54, s2, 0x4000
	s_cmp_lg_u32 s48, 2
	s_cselect_b32 s54, s54, 0
	s_add_i32 s55, s54, s41
	s_add_i32 s55, s55, 0xc000
	s_add_i32 s54, s54, s42
	s_add_i32 s54, s54, 0xc000
.LBB0_291:
	v_add_u32_e32 v0, s2, v199
	ds_read_b128 v[130:133], v0
	s_add_i32 s0, s47, -2
	ds_read_b128 v[188:191], v0 offset:1024
	s_setprio 1
	s_waitcnt lgkmcnt(1)
	v_mfma_f32_32x32x16_bf16 v[130:145], v[130:133], v[146:149], 0
	s_setprio 0
	ds_read_b128 v[248:251], v0 offset:2048
	s_setprio 1
	s_waitcnt lgkmcnt(1)
	v_mfma_f32_32x32x16_bf16 v[130:145], v[188:191], v[150:153], v[130:145]
	s_setprio 0
	ds_read_b128 v[188:191], v0 offset:3072
	s_cmp_lt_u32 s47, s44
	s_cbranch_scc0 .Lmy_a_nok1
	s_mov_b32 m0, s52
	s_nop 0
	global_load_lds_dwordx4 v[210:211], off
.Lmy_a_nok1:
	s_setprio 1
	s_waitcnt lgkmcnt(1)
	v_mfma_f32_32x32x16_bf16 v[130:145], v[248:251], v[154:157], v[130:145]
	s_setprio 0
	ds_read_b128 v[248:251], v0 offset:4096
	s_setprio 1
	s_waitcnt lgkmcnt(1)
	v_mfma_f32_32x32x16_bf16 v[130:145], v[188:191], v[158:161], v[130:145]
	s_setprio 0
	ds_read_b128 v[188:191], v0 offset:5120
	s_setprio 1
	s_waitcnt lgkmcnt(1)
	v_mfma_f32_32x32x16_bf16 v[130:145], v[248:251], v[162:165], v[130:145]
	s_setprio 0
	ds_read_b128 v[248:251], v0 offset:6144
	s_cmp_lt_u32 s47, s44
	s_cbranch_scc0 .Lmy_a_nok2
	s_mov_b32 m0, s53
	s_nop 0
	global_load_lds_dwordx4 v[208:209], off
.Lmy_a_nok2:
	s_setprio 1
	s_waitcnt lgkmcnt(1)
	v_mfma_f32_32x32x16_bf16 v[130:145], v[188:191], v[166:169], v[130:145]
	s_setprio 0
	ds_read_b128 v[188:191], v0 offset:7168
	s_setprio 1
	s_waitcnt lgkmcnt(1)
	v_mfma_f32_32x32x16_bf16 v[130:145], v[248:251], v[170:173], v[130:145]
	s_setprio 0
	s_setprio 1
	s_waitcnt lgkmcnt(0)
	v_mfma_f32_32x32x16_bf16 v[130:145], v[188:191], v[174:177], v[130:145]
	s_setprio 0
	s_cmp_lt_u32 s0, s43
	s_cbranch_scc1 .LBB0_293
	v_add_u32_e32 v0, s46, v223
	v_add_u32_e32 v187, 32, v0
	v_cmp_lt_u32_e32 vcc, v187, v201
	s_nop 5
	v_cndmask_b32_e32 v131, v246, v131, vcc
	v_cmp_le_u32_e32 vcc, v187, v201
	v_add_u32_e32 v187, 34, v0
	s_nop 0
	v_cndmask_b32_e32 v130, v246, v130, vcc
	v_cmp_le_u32_e32 vcc, v187, v201
	v_add_u32_e32 v187, 35, v0
	s_nop 0
	v_cndmask_b32_e32 v132, v246, v132, vcc
	v_cmp_le_u32_e32 vcc, v187, v201
	v_add_u32_e32 v187, 40, v0
	s_nop 0
	v_cndmask_b32_e32 v133, v246, v133, vcc
	v_cmp_le_u32_e32 vcc, v187, v201
	v_add_u32_e32 v187, 41, v0
	s_nop 0
	v_cndmask_b32_e32 v134, v246, v134, vcc
	v_cmp_le_u32_e32 vcc, v187, v201
	v_add_u32_e32 v187, 42, v0
	s_nop 0
	v_cndmask_b32_e32 v135, v246, v135, vcc
	v_cmp_le_u32_e32 vcc, v187, v201
	v_add_u32_e32 v187, 43, v0
	s_nop 0
	v_cndmask_b32_e32 v136, v246, v136, vcc
	v_cmp_le_u32_e32 vcc, v187, v201
	v_add_u32_e32 v187, 48, v0
	s_nop 0
	v_cndmask_b32_e32 v137, v246, v137, vcc
	v_cmp_le_u32_e32 vcc, v187, v201
	v_add_u32_e32 v187, 49, v0
	s_nop 0
	v_cndmask_b32_e32 v138, v246, v138, vcc
	v_cmp_le_u32_e32 vcc, v187, v201
	v_add_u32_e32 v187, 50, v0
	s_nop 0
	v_cndmask_b32_e32 v139, v246, v139, vcc
	v_cmp_le_u32_e32 vcc, v187, v201
	v_add_u32_e32 v187, 51, v0
	s_nop 0
	v_cndmask_b32_e32 v140, v246, v140, vcc
	v_cmp_le_u32_e32 vcc, v187, v201
	v_add_u32_e32 v187, 56, v0
	s_nop 0
	v_cndmask_b32_e32 v141, v246, v141, vcc
	v_cmp_le_u32_e32 vcc, v187, v201
	v_add_u32_e32 v187, 57, v0
	s_nop 0
	v_cndmask_b32_e32 v142, v246, v142, vcc
	v_cmp_le_u32_e32 vcc, v187, v201
	v_add_u32_e32 v187, 58, v0
	v_add_u32_e32 v0, 59, v0
	v_cndmask_b32_e32 v143, v246, v143, vcc
	v_cmp_le_u32_e32 vcc, v187, v201
	s_nop 1
	v_cndmask_b32_e32 v144, v246, v144, vcc
	v_cmp_le_u32_e32 vcc, v0, v201
	s_nop 1
	v_cndmask_b32_e32 v145, v246, v145, vcc
.LBB0_293:
	s_nop 8
	v_max_f32_e32 v0, v131, v131
	v_max_f32_e32 v187, v130, v130
	v_max_f32_e32 v0, v187, v0
	v_max_f32_e32 v187, v133, v133
	v_max_f32_e32 v188, v132, v132
	v_max_f32_e32 v187, v188, v187
	v_max_f32_e32 v188, v137, v137
	v_max_f32_e32 v189, v136, v136
	v_max_f32_e32 v188, v189, v188
	v_max3_f32 v188, v134, v135, v188
	v_max3_f32 v0, v0, v187, v188
	v_max_f32_e32 v187, v141, v141
	v_max_f32_e32 v188, v140, v140
	v_max_f32_e32 v187, v188, v187
	v_max_f32_e32 v188, v145, v145
	v_max_f32_e32 v189, v144, v144
	v_max_f32_e32 v188, v189, v188
	v_max3_f32 v187, v138, v139, v187
	v_max3_f32 v188, v142, v143, v188
	v_max3_f32 v0, v0, v187, v188
	v_mov_b32_e32 v187, v0
	s_nop 1
	v_permlane32_swap_b32_e32 v0, v187
	v_max_f32_e32 v187, v187, v187
	v_max_f32_e32 v0, v0, v0
	s_lshl_b32 s0, s49, 14
	v_max_f32_e32 v0, v0, v187
	v_add_f32_e32 v187, 0x41000000, v186
	s_add_i32 s3, s0, 0
	v_cmp_gt_f32_e32 vcc, v0, v187
	s_cmp_eq_u64 vcc, 0
	v_max_f32_e32 v187, v186, v186
	v_max_f32_e32 v0, v187, v0
	s_cselect_b64 s[0:1], -1, 0
	v_cndmask_b32_e64 v0, v0, v186, s[0:1]
	v_add_u32_e32 v252, s3, v224
	v_sub_f32_e32 v247, v186, v0
	v_add_u32_e32 v253, s3, v228
	ds_read_b64_tr_b16 v[186:187], v252 offset:49152
	ds_read_b64_tr_b16 v[188:189], v252 offset:53248
	ds_read_b64_tr_b16 v[190:191], v253 offset:49152
	ds_read_b64_tr_b16 v[192:193], v253 offset:53248
	v_exp_f32_e32 v247, v247
	v_add_u32_e32 v254, s3, v229
	ds_read_b64_tr_b16 v[248:249], v254 offset:49152
	ds_read_b64_tr_b16 v[250:251], v254 offset:53248
	s_setprio 1
	s_waitcnt lgkmcnt(4)
	v_mfma_f32_32x32x16_bf16 v[114:129], v[182:185], v[186:189], v[114:129]
	s_setprio 0
	v_add_u32_e32 v195, s3, v230
	ds_read_b64_tr_b16 v[186:187], v195 offset:49152
	ds_read_b64_tr_b16 v[188:189], v195 offset:53248
	v_sub_f32_e32 v130, v130, v0
	v_exp_f32_e32 v1, v130
	s_setprio 1
	s_waitcnt lgkmcnt(4)
	v_mfma_f32_32x32x16_bf16 v[98:113], v[182:185], v[190:193], v[98:113]
	s_setprio 0
	ds_read_b64_tr_b16 v[190:191], v252 offset:49408
	ds_read_b64_tr_b16 v[192:193], v252 offset:53504
	v_sub_f32_e32 v131, v131, v0
	v_exp_f32_e32 v131, v131
	v_add_f32_e32 v130, 0, v1
	s_setprio 1
	s_waitcnt lgkmcnt(4)
	v_mfma_f32_32x32x16_bf16 v[82:97], v[182:185], v[248:251], v[82:97]
	s_setprio 0
	ds_read_b64_tr_b16 v[248:249], v253 offset:49408
	ds_read_b64_tr_b16 v[250:251], v253 offset:53504
	v_sub_f32_e32 v132, v132, v0
	v_exp_f32_e32 v132, v132
	v_add_f32_e32 v130, v131, v130
	s_setprio 1
	s_waitcnt lgkmcnt(4)
	v_mfma_f32_32x32x16_bf16 v[66:81], v[182:185], v[186:189], v[66:81]
	s_setprio 0
	ds_read_b64_tr_b16 v[186:187], v254 offset:49408
	ds_read_b64_tr_b16 v[188:189], v254 offset:53504
	v_sub_f32_e32 v133, v133, v0
	v_exp_f32_e32 v133, v133
	v_add_f32_e32 v130, v132, v130
	s_cmp_le_u32 s47, s44
	s_cbranch_scc0 .Lmy_a_nov1
	s_mov_b32 m0, s54
	s_nop 0
	global_load_lds_dwordx4 v[206:207], off
.Lmy_a_nov1:
	s_setprio 1
	s_waitcnt lgkmcnt(4)
	v_mfma_f32_32x32x16_bf16 v[50:65], v[182:185], v[190:193], v[50:65]
	s_setprio 0
	ds_read_b64_tr_b16 v[190:191], v195 offset:49408
	ds_read_b64_tr_b16 v[192:193], v195 offset:53504
	v_sub_f32_e32 v134, v134, v0
	v_exp_f32_e32 v134, v134
	v_add_f32_e32 v130, v133, v130
	s_setprio 1
	s_waitcnt lgkmcnt(4)
	v_mfma_f32_32x32x16_bf16 v[34:49], v[182:185], v[248:251], v[34:49]
	s_setprio 0
	ds_read_b64_tr_b16 v[248:249], v252 offset:57344
	ds_read_b64_tr_b16 v[250:251], v252 offset:61440
	v_sub_f32_e32 v135, v135, v0
	v_exp_f32_e32 v135, v135
	v_add_f32_e32 v130, v134, v130
	s_setprio 1
	s_waitcnt lgkmcnt(4)
	v_mfma_f32_32x32x16_bf16 v[18:33], v[182:185], v[186:189], v[18:33]
	s_setprio 0
	ds_read_b64_tr_b16 v[186:187], v253 offset:57344
	ds_read_b64_tr_b16 v[188:189], v253 offset:61440
	v_sub_f32_e32 v136, v136, v0
	v_exp_f32_e32 v136, v136
	v_add_f32_e32 v130, v135, v130
	s_setprio 1
	s_waitcnt lgkmcnt(4)
	v_mfma_f32_32x32x16_bf16 v[2:17], v[182:185], v[190:193], v[2:17]
	s_setprio 0
	ds_read_b64_tr_b16 v[182:183], v254 offset:57344
	ds_read_b64_tr_b16 v[184:185], v254 offset:61440
	v_sub_f32_e32 v137, v137, v0
	v_exp_f32_e32 v137, v137
	v_add_f32_e32 v130, v136, v130
	s_setprio 1
	s_waitcnt lgkmcnt(4)
	v_mfma_f32_32x32x16_bf16 v[114:129], v[178:181], v[248:251], v[114:129]
	s_setprio 0
	ds_read_b64_tr_b16 v[190:191], v195 offset:57344
	ds_read_b64_tr_b16 v[192:193], v195 offset:61440
	v_sub_f32_e32 v138, v138, v0
	v_exp_f32_e32 v138, v138
	v_add_f32_e32 v130, v137, v130
	s_setprio 1
	s_waitcnt lgkmcnt(4)
	v_mfma_f32_32x32x16_bf16 v[98:113], v[178:181], v[186:189], v[98:113]
	s_setprio 0
	ds_read_b64_tr_b16 v[186:187], v252 offset:57600
	ds_read_b64_tr_b16 v[188:189], v252 offset:61696
	v_sub_f32_e32 v139, v139, v0
	v_exp_f32_e32 v139, v139
	v_add_f32_e32 v130, v138, v130
	s_cmp_le_u32 s47, s44
	s_cbranch_scc0 .Lmy_a_nov2
	s_mov_b32 m0, s55
	s_nop 0
	global_load_lds_dwordx4 v[204:205], off
.Lmy_a_nov2:
	s_setprio 1
	s_waitcnt lgkmcnt(4)
	v_mfma_f32_32x32x16_bf16 v[82:97], v[178:181], v[182:185], v[82:97]
	s_setprio 0
	ds_read_b64_tr_b16 v[182:183], v253 offset:57600
	ds_read_b64_tr_b16 v[184:185], v253 offset:61696
	v_sub_f32_e32 v140, v140, v0
	v_exp_f32_e32 v140, v140
	v_add_f32_e32 v130, v139, v130
	s_setprio 1
	s_waitcnt lgkmcnt(4)
	v_mfma_f32_32x32x16_bf16 v[66:81], v[178:181], v[190:193], v[66:81]
	s_setprio 0
	ds_read_b64_tr_b16 v[190:191], v254 offset:57600
	ds_read_b64_tr_b16 v[192:193], v254 offset:61696
	v_sub_f32_e32 v141, v141, v0
	v_exp_f32_e32 v141, v141
	v_add_f32_e32 v130, v140, v130
	s_setprio 1
	s_waitcnt lgkmcnt(4)
	v_mfma_f32_32x32x16_bf16 v[50:65], v[178:181], v[186:189], v[50:65]
	s_setprio 0
	ds_read_b64_tr_b16 v[186:187], v195 offset:57600
	ds_read_b64_tr_b16 v[188:189], v195 offset:61696
	v_sub_f32_e32 v142, v142, v0
	v_exp_f32_e32 v142, v142
	v_add_f32_e32 v130, v141, v130
	s_setprio 1
	s_waitcnt lgkmcnt(4)
	v_mfma_f32_32x32x16_bf16 v[34:49], v[178:181], v[182:185], v[34:49]
	s_setprio 0
	v_sub_f32_e32 v143, v143, v0
	v_exp_f32_e32 v143, v143
	v_add_f32_e32 v130, v142, v130
	s_setprio 1
	s_waitcnt lgkmcnt(2)
	v_mfma_f32_32x32x16_bf16 v[18:33], v[178:181], v[190:193], v[18:33]
	s_setprio 0
	v_sub_f32_e32 v144, v144, v0
	v_exp_f32_e32 v144, v144
	v_add_f32_e32 v130, v143, v130
	s_setprio 1
	s_waitcnt lgkmcnt(0)
	v_mfma_f32_32x32x16_bf16 v[2:17], v[178:181], v[186:189], v[2:17]
	s_setprio 0
	v_sub_f32_e32 v145, v145, v0
	v_exp_f32_e32 v145, v145
	v_add_f32_e32 v130, v144, v130
	s_cbranch_vccz .LBB0_295
	ds_write_b32 v226, v247
	ds_read_b128 v[190:193], v227 offset:96
	ds_read_b128 v[186:189], v227 offset:64
	ds_read_b128 v[182:185], v227 offset:32
	ds_read_b128 v[178:181], v227
	s_waitcnt lgkmcnt(3)
	v_pk_mul_f32 v[128:129], v[128:129], v[192:193]
	s_waitcnt lgkmcnt(2)
	v_pk_mul_f32 v[124:125], v[124:125], v[188:189]
	s_waitcnt lgkmcnt(1)
	v_pk_mul_f32 v[120:121], v[120:121], v[184:185]
	s_waitcnt lgkmcnt(0)
	v_pk_mul_f32 v[116:117], v[116:117], v[180:181]
	v_pk_mul_f32 v[126:127], v[126:127], v[190:191]
	v_pk_mul_f32 v[122:123], v[122:123], v[186:187]
	v_pk_mul_f32 v[118:119], v[118:119], v[182:183]
	v_pk_mul_f32 v[114:115], v[114:115], v[178:179]
	v_pk_mul_f32 v[112:113], v[112:113], v[192:193]
	v_pk_mul_f32 v[108:109], v[108:109], v[188:189]
	v_pk_mul_f32 v[104:105], v[104:105], v[184:185]
	v_pk_mul_f32 v[100:101], v[100:101], v[180:181]
	v_pk_mul_f32 v[110:111], v[110:111], v[190:191]
	v_pk_mul_f32 v[106:107], v[106:107], v[186:187]
	v_pk_mul_f32 v[102:103], v[102:103], v[182:183]
	v_pk_mul_f32 v[98:99], v[98:99], v[178:179]
	v_pk_mul_f32 v[96:97], v[96:97], v[192:193]
	v_pk_mul_f32 v[92:93], v[92:93], v[188:189]
	v_pk_mul_f32 v[88:89], v[88:89], v[184:185]
	v_pk_mul_f32 v[84:85], v[84:85], v[180:181]
	v_pk_mul_f32 v[94:95], v[94:95], v[190:191]
	v_pk_mul_f32 v[90:91], v[90:91], v[186:187]
	v_pk_mul_f32 v[86:87], v[86:87], v[182:183]
	v_pk_mul_f32 v[82:83], v[82:83], v[178:179]
	v_pk_mul_f32 v[80:81], v[80:81], v[192:193]
	v_pk_mul_f32 v[76:77], v[76:77], v[188:189]
	v_pk_mul_f32 v[72:73], v[72:73], v[184:185]
	v_pk_mul_f32 v[68:69], v[68:69], v[180:181]
	v_pk_mul_f32 v[78:79], v[78:79], v[190:191]
	v_pk_mul_f32 v[74:75], v[74:75], v[186:187]
	v_pk_mul_f32 v[70:71], v[70:71], v[182:183]
	v_pk_mul_f32 v[66:67], v[66:67], v[178:179]
	v_pk_mul_f32 v[64:65], v[64:65], v[192:193]
	v_pk_mul_f32 v[60:61], v[60:61], v[188:189]
	v_pk_mul_f32 v[56:57], v[56:57], v[184:185]
	v_pk_mul_f32 v[52:53], v[52:53], v[180:181]
	v_pk_mul_f32 v[62:63], v[62:63], v[190:191]
	v_pk_mul_f32 v[58:59], v[58:59], v[186:187]
	v_pk_mul_f32 v[54:55], v[54:55], v[182:183]
	v_pk_mul_f32 v[50:51], v[50:51], v[178:179]
	v_pk_mul_f32 v[48:49], v[48:49], v[192:193]
	v_pk_mul_f32 v[44:45], v[44:45], v[188:189]
	v_pk_mul_f32 v[40:41], v[40:41], v[184:185]
	v_pk_mul_f32 v[36:37], v[36:37], v[180:181]
	v_pk_mul_f32 v[46:47], v[46:47], v[190:191]
	v_pk_mul_f32 v[42:43], v[42:43], v[186:187]
	v_pk_mul_f32 v[38:39], v[38:39], v[182:183]
	v_pk_mul_f32 v[34:35], v[34:35], v[178:179]
	v_pk_mul_f32 v[32:33], v[32:33], v[192:193]
	v_pk_mul_f32 v[28:29], v[28:29], v[188:189]
	v_pk_mul_f32 v[24:25], v[24:25], v[184:185]
	v_pk_mul_f32 v[20:21], v[20:21], v[180:181]
	v_pk_mul_f32 v[30:31], v[30:31], v[190:191]
	v_pk_mul_f32 v[26:27], v[26:27], v[186:187]
	v_pk_mul_f32 v[22:23], v[22:23], v[182:183]
	v_pk_mul_f32 v[18:19], v[18:19], v[178:179]
	v_pk_mul_f32 v[16:17], v[16:17], v[192:193]
	v_pk_mul_f32 v[12:13], v[12:13], v[188:189]
	v_pk_mul_f32 v[8:9], v[8:9], v[184:185]
	v_pk_mul_f32 v[4:5], v[4:5], v[180:181]
	v_pk_mul_f32 v[14:15], v[14:15], v[190:191]
	v_pk_mul_f32 v[10:11], v[10:11], v[186:187]
	v_pk_mul_f32 v[6:7], v[6:7], v[182:183]
	v_pk_mul_f32 v[2:3], v[2:3], v[178:179]

.LBB0_1605:
	s_mov_b32 s46, s0
	s_cmp_lt_u32 s45, s42
	s_cbranch_scc0 .Lmy_b_drain
	s_waitcnt vmcnt(4)
	s_barrier
	s_branch .Lmy_b_go

.Lmy_b_go:
	s_lshl_b32 s2, s46, 14
	s_lshl_b32 s52, s47, 14
	s_add_i32 s52, s4, s52
	s_add_i32 s53, s52, 0x2000
	s_add_i32 s54, s2, 0x4000
	s_cmp_lg_u32 s46, 2
	s_cselect_b32 s54, s54, 0
	s_add_i32 s55, s54, s39
	s_add_i32 s55, s55, 0xc000
	s_add_i32 s54, s54, s40
	s_add_i32 s54, s54, 0xc000
.LBB0_1615:
	v_add_u32_e32 v0, s2, v199
	ds_read_b128 v[130:133], v0
	s_add_i32 s0, s45, -2
	ds_read_b128 v[188:191], v0 offset:1024
	s_setprio 1
	s_waitcnt lgkmcnt(1)
	v_mfma_f32_32x32x16_bf16 v[130:145], v[130:133], v[146:149], 0
	s_setprio 0
	ds_read_b128 v[248:251], v0 offset:2048
	s_setprio 1
	s_waitcnt lgkmcnt(1)
	v_mfma_f32_32x32x16_bf16 v[130:145], v[188:191], v[150:153], v[130:145]
	s_setprio 0
	ds_read_b128 v[188:191], v0 offset:3072
	s_cmp_lt_u32 s45, s42
	s_cbranch_scc0 .Lmy_b_nok1
	s_mov_b32 m0, s52
	s_nop 0
	global_load_lds_dwordx4 v[210:211], off
.Lmy_b_nok1:
	s_setprio 1
	s_waitcnt lgkmcnt(1)
	v_mfma_f32_32x32x16_bf16 v[130:145], v[248:251], v[154:157], v[130:145]
	s_setprio 0
	ds_read_b128 v[248:251], v0 offset:4096
	s_setprio 1
	s_waitcnt lgkmcnt(1)
	v_mfma_f32_32x32x16_bf16 v[130:145], v[188:191], v[158:161], v[130:145]
	s_setprio 0
	ds_read_b128 v[188:191], v0 offset:5120
	s_setprio 1
	s_waitcnt lgkmcnt(1)
	v_mfma_f32_32x32x16_bf16 v[130:145], v[248:251], v[162:165], v[130:145]
	s_setprio 0
	ds_read_b128 v[248:251], v0 offset:6144
	s_cmp_lt_u32 s45, s42
	s_cbranch_scc0 .Lmy_b_nok2
	s_mov_b32 m0, s53
	s_nop 0
	global_load_lds_dwordx4 v[208:209], off
.Lmy_b_nok2:
	s_setprio 1
	s_waitcnt lgkmcnt(1)
	v_mfma_f32_32x32x16_bf16 v[130:145], v[188:191], v[166:169], v[130:145]
	s_setprio 0
	ds_read_b128 v[188:191], v0 offset:7168
	s_setprio 1
	s_waitcnt lgkmcnt(1)
	v_mfma_f32_32x32x16_bf16 v[130:145], v[248:251], v[170:173], v[130:145]
	s_setprio 0
	s_setprio 1
	s_waitcnt lgkmcnt(0)
	v_mfma_f32_32x32x16_bf16 v[130:145], v[188:191], v[174:177], v[130:145]
	s_setprio 0
	s_cmp_lt_u32 s0, s41
	s_cbranch_scc1 .LBB0_1617
	v_add_u32_e32 v0, s44, v223
	v_add_u32_e32 v187, 32, v0
	v_cmp_lt_u32_e32 vcc, v187, v201
	s_nop 5
	v_cndmask_b32_e32 v131, v246, v131, vcc
	v_cmp_le_u32_e32 vcc, v187, v201
	v_add_u32_e32 v187, 34, v0
	s_nop 0
	v_cndmask_b32_e32 v130, v246, v130, vcc
	v_cmp_le_u32_e32 vcc, v187, v201
	v_add_u32_e32 v187, 35, v0
	s_nop 0
	v_cndmask_b32_e32 v132, v246, v132, vcc
	v_cmp_le_u32_e32 vcc, v187, v201
	v_add_u32_e32 v187, 40, v0
	s_nop 0
	v_cndmask_b32_e32 v133, v246, v133, vcc
	v_cmp_le_u32_e32 vcc, v187, v201
	v_add_u32_e32 v187, 41, v0
	s_nop 0
	v_cndmask_b32_e32 v134, v246, v134, vcc
	v_cmp_le_u32_e32 vcc, v187, v201
	v_add_u32_e32 v187, 42, v0
	s_nop 0
	v_cndmask_b32_e32 v135, v246, v135, vcc
	v_cmp_le_u32_e32 vcc, v187, v201
	v_add_u32_e32 v187, 43, v0
	s_nop 0
	v_cndmask_b32_e32 v136, v246, v136, vcc
	v_cmp_le_u32_e32 vcc, v187, v201
	v_add_u32_e32 v187, 48, v0
	s_nop 0
	v_cndmask_b32_e32 v137, v246, v137, vcc
	v_cmp_le_u32_e32 vcc, v187, v201
	v_add_u32_e32 v187, 49, v0
	s_nop 0
	v_cndmask_b32_e32 v138, v246, v138, vcc
	v_cmp_le_u32_e32 vcc, v187, v201
	v_add_u32_e32 v187, 50, v0
	s_nop 0
	v_cndmask_b32_e32 v139, v246, v139, vcc
	v_cmp_le_u32_e32 vcc, v187, v201
	v_add_u32_e32 v187, 51, v0
	s_nop 0
	v_cndmask_b32_e32 v140, v246, v140, vcc
	v_cmp_le_u32_e32 vcc, v187, v201
	v_add_u32_e32 v187, 56, v0
	s_nop 0
	v_cndmask_b32_e32 v141, v246, v141, vcc
	v_cmp_le_u32_e32 vcc, v187, v201
	v_add_u32_e32 v187, 57, v0
	s_nop 0
	v_cndmask_b32_e32 v142, v246, v142, vcc
	v_cmp_le_u32_e32 vcc, v187, v201
	v_add_u32_e32 v187, 58, v0
	v_add_u32_e32 v0, 59, v0
	v_cndmask_b32_e32 v143, v246, v143, vcc
	v_cmp_le_u32_e32 vcc, v187, v201
	s_nop 1
	v_cndmask_b32_e32 v144, v246, v144, vcc
	v_cmp_le_u32_e32 vcc, v0, v201
	s_nop 1
	v_cndmask_b32_e32 v145, v246, v145, vcc
.LBB0_1617:
	s_nop 8
	v_max_f32_e32 v0, v131, v131
	v_max_f32_e32 v187, v130, v130
	v_max_f32_e32 v0, v187, v0
	v_max_f32_e32 v187, v133, v133
	v_max_f32_e32 v188, v132, v132
	v_max_f32_e32 v187, v188, v187
	v_max_f32_e32 v188, v137, v137
	v_max_f32_e32 v189, v136, v136
	v_max_f32_e32 v188, v189, v188
	v_max3_f32 v188, v134, v135, v188
	v_max3_f32 v0, v0, v187, v188
	v_max_f32_e32 v187, v141, v141
	v_max_f32_e32 v188, v140, v140
	v_max_f32_e32 v187, v188, v187
	v_max_f32_e32 v188, v145, v145
	v_max_f32_e32 v189, v144, v144
	v_max_f32_e32 v188, v189, v188
	v_max3_f32 v187, v138, v139, v187
	v_max3_f32 v188, v142, v143, v188
	v_max3_f32 v0, v0, v187, v188
	v_mov_b32_e32 v187, v0
	s_nop 1
	v_permlane32_swap_b32_e32 v0, v187
	v_max_f32_e32 v187, v187, v187
	v_max_f32_e32 v0, v0, v0
	s_lshl_b32 s0, s47, 14
	v_max_f32_e32 v0, v0, v187
	v_add_f32_e32 v187, 0x41000000, v186
	s_add_i32 s3, s0, 0
	v_cmp_gt_f32_e32 vcc, v0, v187
	s_cmp_eq_u64 vcc, 0
	v_max_f32_e32 v187, v186, v186
	v_max_f32_e32 v0, v187, v0
	s_cselect_b64 s[0:1], -1, 0
	v_cndmask_b32_e64 v0, v0, v186, s[0:1]
	v_add_u32_e32 v252, s3, v224
	v_sub_f32_e32 v247, v186, v0
	v_add_u32_e32 v253, s3, v228
	ds_read_b64_tr_b16 v[186:187], v252 offset:49152
	ds_read_b64_tr_b16 v[188:189], v252 offset:53248
	ds_read_b64_tr_b16 v[190:191], v253 offset:49152
	ds_read_b64_tr_b16 v[192:193], v253 offset:53248
	v_exp_f32_e32 v247, v247
	v_add_u32_e32 v254, s3, v229
	ds_read_b64_tr_b16 v[248:249], v254 offset:49152
	ds_read_b64_tr_b16 v[250:251], v254 offset:53248
	s_setprio 1
	s_waitcnt lgkmcnt(4)
	v_mfma_f32_32x32x16_bf16 v[114:129], v[182:185], v[186:189], v[114:129]
	s_setprio 0
	v_add_u32_e32 v195, s3, v230
	ds_read_b64_tr_b16 v[186:187], v195 offset:49152
	ds_read_b64_tr_b16 v[188:189], v195 offset:53248
	v_sub_f32_e32 v130, v130, v0
	v_exp_f32_e32 v1, v130
	s_setprio 1
	s_waitcnt lgkmcnt(4)
	v_mfma_f32_32x32x16_bf16 v[98:113], v[182:185], v[190:193], v[98:113]
	s_setprio 0
	ds_read_b64_tr_b16 v[190:191], v252 offset:49408
	ds_read_b64_tr_b16 v[192:193], v252 offset:53504
	v_sub_f32_e32 v131, v131, v0
	v_exp_f32_e32 v131, v131
	v_add_f32_e32 v130, 0, v1
	s_setprio 1
	s_waitcnt lgkmcnt(4)
	v_mfma_f32_32x32x16_bf16 v[82:97], v[182:185], v[248:251], v[82:97]
	s_setprio 0
	ds_read_b64_tr_b16 v[248:249], v253 offset:49408
	ds_read_b64_tr_b16 v[250:251], v253 offset:53504
	v_sub_f32_e32 v132, v132, v0
	v_exp_f32_e32 v132, v132
	v_add_f32_e32 v130, v131, v130
	s_setprio 1
	s_waitcnt lgkmcnt(4)
	v_mfma_f32_32x32x16_bf16 v[66:81], v[182:185], v[186:189], v[66:81]
	s_setprio 0
	ds_read_b64_tr_b16 v[186:187], v254 offset:49408
	ds_read_b64_tr_b16 v[188:189], v254 offset:53504
	v_sub_f32_e32 v133, v133, v0
	v_exp_f32_e32 v133, v133
	v_add_f32_e32 v130, v132, v130
	s_cmp_le_u32 s45, s42
	s_cbranch_scc0 .Lmy_b_nov1
	s_mov_b32 m0, s54
	s_nop 0
	global_load_lds_dwordx4 v[206:207], off
.Lmy_b_nov1:
	s_setprio 1
	s_waitcnt lgkmcnt(4)
	v_mfma_f32_32x32x16_bf16 v[50:65], v[182:185], v[190:193], v[50:65]
	s_setprio 0
	ds_read_b64_tr_b16 v[190:191], v195 offset:49408
	ds_read_b64_tr_b16 v[192:193], v195 offset:53504
	v_sub_f32_e32 v134, v134, v0
	v_exp_f32_e32 v134, v134
	v_add_f32_e32 v130, v133, v130
	s_setprio 1
	s_waitcnt lgkmcnt(4)
	v_mfma_f32_32x32x16_bf16 v[34:49], v[182:185], v[248:251], v[34:49]
	s_setprio 0
	ds_read_b64_tr_b16 v[248:249], v252 offset:57344
	ds_read_b64_tr_b16 v[250:251], v252 offset:61440
	v_sub_f32_e32 v135, v135, v0
	v_exp_f32_e32 v135, v135
	v_add_f32_e32 v130, v134, v130
	s_setprio 1
	s_waitcnt lgkmcnt(4)
	v_mfma_f32_32x32x16_bf16 v[18:33], v[182:185], v[186:189], v[18:33]
	s_setprio 0
	ds_read_b64_tr_b16 v[186:187], v253 offset:57344
	ds_read_b64_tr_b16 v[188:189], v253 offset:61440
	v_sub_f32_e32 v136, v136, v0
	v_exp_f32_e32 v136, v136
	v_add_f32_e32 v130, v135, v130
	s_setprio 1
	s_waitcnt lgkmcnt(4)
	v_mfma_f32_32x32x16_bf16 v[2:17], v[182:185], v[190:193], v[2:17]
	s_setprio 0
	ds_read_b64_tr_b16 v[182:183], v254 offset:57344
	ds_read_b64_tr_b16 v[184:185], v254 offset:61440
	v_sub_f32_e32 v137, v137, v0
	v_exp_f32_e32 v137, v137
	v_add_f32_e32 v130, v136, v130
	s_setprio 1
	s_waitcnt lgkmcnt(4)
	v_mfma_f32_32x32x16_bf16 v[114:129], v[178:181], v[248:251], v[114:129]
	s_setprio 0
	ds_read_b64_tr_b16 v[190:191], v195 offset:57344
	ds_read_b64_tr_b16 v[192:193], v195 offset:61440
	v_sub_f32_e32 v138, v138, v0
	v_exp_f32_e32 v138, v138
	v_add_f32_e32 v130, v137, v130
	s_setprio 1
	s_waitcnt lgkmcnt(4)
	v_mfma_f32_32x32x16_bf16 v[98:113], v[178:181], v[186:189], v[98:113]
	s_setprio 0
	ds_read_b64_tr_b16 v[186:187], v252 offset:57600
	ds_read_b64_tr_b16 v[188:189], v252 offset:61696
	v_sub_f32_e32 v139, v139, v0
	v_exp_f32_e32 v139, v139
	v_add_f32_e32 v130, v138, v130
	s_cmp_le_u32 s45, s42
	s_cbranch_scc0 .Lmy_b_nov2
	s_mov_b32 m0, s55
	s_nop 0
	global_load_lds_dwordx4 v[204:205], off
